# spatial prepass: 128 serialized 2-byte loads per thread replaced by 8 groups of 16 global loads (3 rotating banks, counted vmcnt), same fmac order; plus NA QK/PV LDS read pipelining
# speedup vs baseline: 1.0453x; 1.0169x over previous
.LBB0_751:
	v_lshl_add_u64 v[54:55], vcc, 0, v[192:193]
	v_mad_i64_i32 v[50:51], vcc, s96, v188, 0
	v_lshl_add_u64 v[50:51], v[50:51], 1, v[48:49]
	v_lshl_add_u64 v[50:51], v[164:165], 1, v[50:51]
	global_load_dwordx4 v[148:151], v[50:51], off
	v_mad_i64_i32 v[50:51], vcc, s94, v166, 0
	v_lshl_add_u64 v[50:51], v[50:51], 1, v[54:55]
	global_load_dwordx4 v[144:147], v[50:51], off
	v_mad_i64_i32 v[50:51], vcc, s96, v189, 0
	v_lshl_add_u64 v[50:51], v[50:51], 1, v[48:49]
	v_lshl_add_u64 v[50:51], v[168:169], 1, v[50:51]
	global_load_dwordx4 v[140:143], v[50:51], off
	v_mad_i64_i32 v[50:51], vcc, s94, v170, 0
	v_lshl_add_u64 v[50:51], v[50:51], 1, v[54:55]
	global_load_dwordx4 v[132:135], v[50:51], off
	v_mad_i64_i32 v[50:51], vcc, s96, v190, 0
	v_mad_i64_i32 v[56:57], s[96:97], s96, v191, 0
	v_lshl_add_u64 v[50:51], v[50:51], 1, v[48:49]
	v_lshl_add_u64 v[48:49], v[56:57], 1, v[48:49]
	v_lshl_add_u64 v[50:51], v[172:173], 1, v[50:51]
	v_lshl_add_u64 v[48:49], v[176:177], 1, v[48:49]
	global_load_dwordx4 v[136:139], v[50:51], off
	global_load_dwordx4 v[156:159], v[48:49], off
	v_mad_i64_i32 v[50:51], vcc, s94, v174, 0
	v_mad_i64_i32 v[48:49], s[94:95], s94, v178, 0
	v_lshl_add_u64 v[50:51], v[50:51], 1, v[54:55]
	v_lshl_add_u64 v[48:49], v[48:49], 1, v[54:55]
	global_load_dwordx4 v[128:131], v[50:51], off
	global_load_dwordx4 v[152:155], v[48:49], off
	s_mul_i32 s47, s47, 0x8400
	v_add_u32_e32 v84, s47, v171
	ds_read_b128 v[240:243], v84
	ds_read_b128 v[244:247], v84 offset:16896
	ds_read_b128 v[248:251], v84 offset:32
	ds_read_b128 v[252:255], v84 offset:16928
	s_waitcnt lgkmcnt(3)
	v_mfma_f32_32x32x16_bf16 v[64:79], v[240:243], v[124:127], v[32:47]
	ds_read_b128 v[240:243], v84 offset:64
	s_waitcnt lgkmcnt(3)
	v_mfma_f32_32x32x16_bf16 v[48:63], v[244:247], v[124:127], v[32:47]
	ds_read_b128 v[244:247], v84 offset:16960
	s_waitcnt lgkmcnt(3)
	v_mfma_f32_32x32x16_bf16 v[64:79], v[248:251], v[120:123], v[64:79]
	ds_read_b128 v[248:251], v84 offset:96
	s_waitcnt lgkmcnt(3)
	v_mfma_f32_32x32x16_bf16 v[48:63], v[252:255], v[120:123], v[48:63]
	ds_read_b128 v[252:255], v84 offset:16992
	s_waitcnt lgkmcnt(3)
	v_mfma_f32_32x32x16_bf16 v[64:79], v[240:243], v[116:119], v[64:79]
	s_waitcnt lgkmcnt(2)
	v_mfma_f32_32x32x16_bf16 v[48:63], v[244:247], v[116:119], v[48:63]
	s_waitcnt lgkmcnt(1)
	v_mfma_f32_32x32x16_bf16 v[64:79], v[248:251], v[112:115], v[64:79]
	s_waitcnt lgkmcnt(0)
	v_mfma_f32_32x32x16_bf16 v[48:63], v[252:255], v[112:115], v[48:63]
	s_cmp_gt_u32 s46, 7
	s_cbranch_scc1 .LBB0_817
	v_add_u32_e32 v229, s90, v228
	v_add_u32_e32 v229, 0x23268, v229
	ds_read2_b32 v[80:81], v229 offset0:32 offset1:33
	ds_read2_b32 v[82:83], v229 offset0:34 offset1:35
	ds_read2_b32 v[84:85], v229 offset0:40 offset1:41
	ds_read2_b32 v[86:87], v229 offset0:42 offset1:43
	ds_read2_b32 v[88:89], v229 offset0:48 offset1:49
	ds_read2_b32 v[90:91], v229 offset0:50 offset1:51
	ds_read2_b32 v[92:93], v229 offset0:56 offset1:57
	ds_read2_b32 v[94:95], v229 offset0:58 offset1:59
	ds_read2_b32 v[96:97], v229 offset0:0 offset1:1
	ds_read2_b32 v[98:99], v229 offset0:2 offset1:3
	ds_read2_b32 v[100:101], v229 offset0:8 offset1:9
	ds_read2_b32 v[102:103], v229 offset0:10 offset1:11
	ds_read2_b32 v[104:105], v229 offset0:16 offset1:17
	ds_read2_b32 v[106:107], v229 offset0:18 offset1:19
	ds_read2_b32 v[108:109], v229 offset0:24 offset1:25
	ds_read2_b32 v[110:111], v229 offset0:26 offset1:27
	v_mov_b32_e32 v230, 0xff800000
	s_waitcnt lgkmcnt(8)
	v_add_f32_e32 v48, v48, v80
	v_cndmask_b32_e64 v48, v230, v48, s[4:5]
	v_add_f32_e32 v49, v49, v81
	v_cndmask_b32_e64 v49, v230, v49, s[42:43]
	v_add_f32_e32 v50, v50, v82
	v_cndmask_b32_e64 v50, v230, v50, s[44:45]
	v_add_f32_e32 v51, v51, v83
	v_cndmask_b32_e64 v51, v230, v51, s[48:49]
	v_add_f32_e32 v52, v52, v84
	v_cndmask_b32_e64 v52, v230, v52, s[50:51]
	v_add_f32_e32 v53, v53, v85
	v_cndmask_b32_e64 v53, v230, v53, s[52:53]
	v_add_f32_e32 v54, v54, v86
	v_cndmask_b32_e64 v54, v230, v54, s[54:55]
	v_add_f32_e32 v55, v55, v87
	v_cndmask_b32_e64 v55, v230, v55, s[58:59]
	v_add_f32_e32 v56, v56, v88
	v_cndmask_b32_e64 v56, v230, v56, s[22:23]
	v_add_f32_e32 v57, v57, v89
	v_cndmask_b32_e64 v57, v230, v57, s[24:25]
	v_add_f32_e32 v58, v58, v90
	v_cndmask_b32_e64 v58, v230, v58, s[26:27]
	v_add_f32_e32 v59, v59, v91
	v_cndmask_b32_e64 v59, v230, v59, s[28:29]
	v_add_f32_e32 v60, v60, v92
	v_cndmask_b32_e64 v60, v230, v60, s[30:31]
	v_add_f32_e32 v61, v61, v93
	v_cndmask_b32_e64 v61, v230, v61, s[34:35]
	v_add_f32_e32 v62, v62, v94
	v_cndmask_b32_e64 v62, v230, v62, s[36:37]
	v_add_f32_e32 v63, v63, v95
	v_cndmask_b32_e64 v63, v230, v63, s[38:39]
	s_waitcnt lgkmcnt(0)
	v_add_f32_e32 v64, v64, v96
	v_cndmask_b32_e64 v64, v230, v64, s[6:7]
	v_add_f32_e32 v65, v65, v97
	v_cndmask_b32_e64 v65, v230, v65, s[8:9]
	v_add_f32_e32 v66, v66, v98
	v_cndmask_b32_e64 v66, v230, v66, s[10:11]
	v_add_f32_e32 v67, v67, v99
	v_cndmask_b32_e64 v67, v230, v67, s[12:13]
	v_add_f32_e32 v68, v68, v100
	v_cndmask_b32_e64 v68, v230, v68, s[14:15]
	v_add_f32_e32 v69, v69, v101
	v_cndmask_b32_e64 v69, v230, v69, s[16:17]
	v_add_f32_e32 v70, v70, v102
	v_cndmask_b32_e64 v70, v230, v70, s[18:19]
	v_add_f32_e32 v71, v71, v103
	v_cndmask_b32_e64 v71, v230, v71, s[20:21]
	v_add_f32_e32 v72, v72, v104
	v_cndmask_b32_e64 v72, v230, v72, s[60:61]
	v_add_f32_e32 v73, v73, v105
	v_cndmask_b32_e64 v73, v230, v73, s[62:63]
	v_add_f32_e32 v74, v74, v106
	v_cndmask_b32_e64 v74, v230, v74, s[68:69]
	v_add_f32_e32 v75, v75, v107
	v_cndmask_b32_e64 v75, v230, v75, s[70:71]
	v_add_f32_e32 v76, v76, v108
	v_cndmask_b32_e64 v76, v230, v76, s[72:73]
	v_add_f32_e32 v77, v77, v109
	v_cndmask_b32_e64 v77, v230, v77, s[80:81]
	v_add_f32_e32 v78, v78, v110
	v_cndmask_b32_e64 v78, v230, v78, s[82:83]
	v_add_f32_e32 v79, v79, v111
	v_cndmask_b32_e64 v79, v230, v79, s[84:85]
.LBB0_817:
	s_nop 8
	v_max_f32_e32 v80, v65, v65
	v_max_f32_e32 v81, v64, v64
	v_max_f32_e32 v80, v81, v80
	v_max3_f32 v81, v66, v67, v49
	v_max3_f32 v80, v80, v48, v50
	v_max3_f32 v80, v80, v51, v68
	v_max3_f32 v81, v81, v70, v71
	v_max3_f32 v80, v80, v69, v52
	v_max3_f32 v81, v81, v54, v55
	v_max3_f32 v80, v80, v53, v72
	v_max3_f32 v81, v81, v74, v75
	v_max3_f32 v80, v80, v73, v56
	v_max3_f32 v81, v81, v58, v59
	v_max3_f32 v80, v80, v57, v76
	v_max3_f32 v81, v81, v78, v79
	v_max3_f32 v80, v80, v77, v60
	v_max3_f32 v81, v81, v62, v63
	v_max3_f32 v80, v80, v61, v81
	v_mov_b32_e32 v81, v80
	s_nop 1
	v_permlane32_swap_b32_e32 v80, v81
	v_max_f32_e32 v81, v81, v81
	v_max_f32_e32 v80, v80, v80
	v_max_f32_e32 v80, v80, v81
	s_mov_b32 s40, 0x40c00000
	v_cmp_lt_f32_e32 vcc, s40, v80
	s_cbranch_vccz .LBB0_819
	v_max_f32_e32 v32, v80, v80
	v_max_f32_e32 v32, 0, v32
	v_exp_f32_e64 v34, -v32
	v_mov_b32_e32 v35, v32
	v_pk_add_f32 v[64:65], v[64:65], v[32:33] op_sel_hi:[1,0] neg_lo:[0,1] neg_hi:[0,1]
	v_pk_add_f32 v[48:49], v[48:49], v[32:33] op_sel_hi:[1,0] neg_lo:[0,1] neg_hi:[0,1]
	v_pk_add_f32 v[96:97], v[180:181], v[34:35]
	v_pk_add_f32 v[66:67], v[66:67], v[32:33] op_sel_hi:[1,0] neg_lo:[0,1] neg_hi:[0,1]
	v_pk_add_f32 v[50:51], v[50:51], v[32:33] op_sel_hi:[1,0] neg_lo:[0,1] neg_hi:[0,1]
	v_pk_add_f32 v[68:69], v[68:69], v[32:33] op_sel_hi:[1,0] neg_lo:[0,1] neg_hi:[0,1]
	v_pk_add_f32 v[52:53], v[52:53], v[32:33] op_sel_hi:[1,0] neg_lo:[0,1] neg_hi:[0,1]
	v_pk_add_f32 v[70:71], v[70:71], v[32:33] op_sel_hi:[1,0] neg_lo:[0,1] neg_hi:[0,1]
	v_pk_add_f32 v[54:55], v[54:55], v[32:33] op_sel_hi:[1,0] neg_lo:[0,1] neg_hi:[0,1]
	v_pk_add_f32 v[72:73], v[72:73], v[32:33] op_sel_hi:[1,0] neg_lo:[0,1] neg_hi:[0,1]
	v_pk_add_f32 v[56:57], v[56:57], v[32:33] op_sel_hi:[1,0] neg_lo:[0,1] neg_hi:[0,1]
	v_pk_add_f32 v[74:75], v[74:75], v[32:33] op_sel_hi:[1,0] neg_lo:[0,1] neg_hi:[0,1]
	v_pk_add_f32 v[58:59], v[58:59], v[32:33] op_sel_hi:[1,0] neg_lo:[0,1] neg_hi:[0,1]
	v_pk_add_f32 v[76:77], v[76:77], v[32:33] op_sel_hi:[1,0] neg_lo:[0,1] neg_hi:[0,1]
	v_pk_add_f32 v[60:61], v[60:61], v[32:33] op_sel_hi:[1,0] neg_lo:[0,1] neg_hi:[0,1]
	v_pk_add_f32 v[78:79], v[78:79], v[32:33] op_sel_hi:[1,0] neg_lo:[0,1] neg_hi:[0,1]
	v_pk_add_f32 v[62:63], v[62:63], v[32:33] op_sel_hi:[1,0] neg_lo:[0,1] neg_hi:[0,1]
	v_pk_mul_f32 v[80:81], v[180:181], v[34:35]
	v_xor_b32_e32 v32, 0x80000000, v97
	v_mov_b32_e32 v81, v97
	v_pk_mul_f32 v[14:15], v[14:15], v[34:35] op_sel_hi:[1,0]
	v_pk_mul_f32 v[12:13], v[12:13], v[34:35] op_sel_hi:[1,0]
	v_pk_mul_f32 v[10:11], v[10:11], v[34:35] op_sel_hi:[1,0]
	v_pk_mul_f32 v[8:9], v[8:9], v[34:35] op_sel_hi:[1,0]
	v_pk_mul_f32 v[6:7], v[6:7], v[34:35] op_sel_hi:[1,0]
	v_pk_mul_f32 v[4:5], v[4:5], v[34:35] op_sel_hi:[1,0]
	v_pk_mul_f32 v[2:3], v[2:3], v[34:35] op_sel_hi:[1,0]
	v_pk_mul_f32 v[0:1], v[0:1], v[34:35] op_sel_hi:[1,0]
	v_pk_mul_f32 v[30:31], v[30:31], v[34:35] op_sel_hi:[1,0]
	v_pk_mul_f32 v[28:29], v[28:29], v[34:35] op_sel_hi:[1,0]
	v_pk_mul_f32 v[26:27], v[26:27], v[34:35] op_sel_hi:[1,0]
	v_pk_mul_f32 v[24:25], v[24:25], v[34:35] op_sel_hi:[1,0]
	v_pk_mul_f32 v[22:23], v[22:23], v[34:35] op_sel_hi:[1,0]
	v_pk_mul_f32 v[20:21], v[20:21], v[34:35] op_sel_hi:[1,0]
	v_pk_mul_f32 v[18:19], v[18:19], v[34:35] op_sel_hi:[1,0]
	v_pk_mul_f32 v[16:17], v[16:17], v[34:35] op_sel_hi:[1,0]
	v_mov_b32_e32 v33, v32
	v_mov_b32_e32 v34, v32
	v_mov_b32_e32 v35, v32
	v_mov_b32_e32 v36, v32
	v_mov_b32_e32 v37, v32
	v_mov_b32_e32 v38, v32
	v_mov_b32_e32 v39, v32
	v_mov_b32_e32 v40, v32
	v_mov_b32_e32 v41, v32
	v_mov_b32_e32 v42, v32
	v_mov_b32_e32 v43, v32
	v_mov_b32_e32 v44, v32
	v_mov_b32_e32 v45, v32
	v_mov_b32_e32 v46, v32
	v_mov_b32_e32 v47, v32
	v_mov_b32_e32 v82, v32
	v_mov_b32_e32 v83, v32
	v_mov_b32_e32 v84, v32
	v_mov_b32_e32 v85, v32
	v_mov_b32_e32 v86, v32
	v_mov_b32_e32 v87, v32
	v_mov_b32_e32 v88, v32
	v_mov_b32_e32 v89, v32
	v_mov_b32_e32 v90, v32
	v_mov_b32_e32 v91, v32
	v_mov_b32_e32 v92, v32
	v_mov_b32_e32 v93, v32
	v_mov_b32_e32 v94, v32
	v_mov_b32_e32 v95, v32
	v_mov_b32_e32 v96, v32
	v_mov_b32_e32 v181, v97
	s_branch .LBB0_820

.LBB0_820:
	v_exp_f32_e32 v64, v64
	v_exp_f32_e32 v65, v65
	v_exp_f32_e32 v48, v48
	v_exp_f32_e32 v49, v49
	v_exp_f32_e32 v66, v66
	v_exp_f32_e32 v67, v67
	v_exp_f32_e32 v50, v50
	v_exp_f32_e32 v51, v51
	v_exp_f32_e32 v68, v68
	v_exp_f32_e32 v69, v69
	v_exp_f32_e32 v102, v52
	v_exp_f32_e32 v103, v53
	v_pk_add_f32 v[98:99], v[64:65], 0 op_sel_hi:[1,0]
	v_pk_add_f32 v[100:101], v[48:49], 0 op_sel_hi:[1,0]
	v_exp_f32_e32 v70, v70
	v_exp_f32_e32 v71, v71
	v_pk_add_f32 v[98:99], v[66:67], v[98:99]
	v_pk_add_f32 v[100:101], v[50:51], v[100:101]
	v_exp_f32_e32 v72, v72
	v_exp_f32_e32 v73, v73
	v_pk_add_f32 v[52:53], v[68:69], v[98:99]
	v_pk_add_f32 v[98:99], v[102:103], v[100:101]
	v_exp_f32_e32 v100, v54
	v_exp_f32_e32 v101, v55
	v_pk_add_f32 v[52:53], v[70:71], v[52:53]
	s_mul_i32 s40, s89, 0x9000
	v_pk_add_f32 v[52:53], v[72:73], v[52:53]
	v_exp_f32_e32 v106, v60
	v_cvt_pk_bf16_f32 v60, v72, v73
	v_add_u32_e32 v72, s40, v175
	v_pk_add_f32 v[54:55], v[100:101], v[98:99]
	v_exp_f32_e32 v98, v56
	v_exp_f32_e32 v99, v57
	v_exp_f32_e32 v104, v58
	v_exp_f32_e32 v105, v59
	v_cvt_pk_bf16_f32 v56, v64, v65
	v_cvt_pk_bf16_f32 v57, v66, v67
	v_cvt_pk_bf16_f32 v58, v68, v69
	v_cvt_pk_bf16_f32 v59, v70, v71
	ds_read_b128 v[64:67], v72
	ds_read_b128 v[68:71], v72 offset:32
	s_waitcnt lgkmcnt(0)
	v_mfma_f32_32x32x16_bf16 v[16:31], v[64:67], v[56:59], v[16:31]
	ds_read_b128 v[240:243], v72 offset:4608
	ds_read_b128 v[244:247], v72 offset:4640
	ds_read_b128 v[248:251], v72 offset:4672
	ds_read_b128 v[252:255], v72 offset:4704
	v_exp_f32_e32 v74, v74
	v_exp_f32_e32 v75, v75
	v_exp_f32_e32 v76, v76
	v_exp_f32_e32 v77, v77
	v_exp_f32_e32 v78, v78
	v_exp_f32_e32 v79, v79
	v_exp_f32_e32 v107, v61
	v_exp_f32_e32 v108, v62
	v_exp_f32_e32 v109, v63
	v_cvt_pk_bf16_f32 v61, v74, v75
	v_cvt_pk_bf16_f32 v62, v76, v77
	v_cvt_pk_bf16_f32 v63, v78, v79
	ds_read_b128 v[64:67], v72 offset:64
	v_pk_add_f32 v[54:55], v[98:99], v[54:55]
	v_mfma_f32_32x32x16_bf16 v[16:31], v[68:71], v[60:63], v[16:31]
	v_add_f32_e64 v52, v74, v52
	v_add_f32_e64 v53, v75, v53
	v_add_f32_e64 v54, v104, v54
	v_add_f32_e64 v55, v105, v55
	v_add_f32_e64 v52, v76, v52
	v_add_f32_e64 v53, v77, v53
	v_pk_add_f32 v[54:55], v[106:107], v[54:55]
	v_pk_add_f32 v[52:53], v[78:79], v[52:53]
	v_pk_add_f32 v[54:55], v[108:109], v[54:55]
	s_add_i32 s40, s91, 1
	v_pk_add_f32 v[52:53], v[54:55], v[52:53]
	v_cvt_pk_bf16_f32 v54, v102, v103
	v_pk_add_f32 v[52:53], v[52:53], v[52:53] op_sel:[0,1] op_sel_hi:[1,0]
	v_cvt_pk_bf16_f32 v55, v100, v101
	v_pk_add_f32 v[80:81], v[80:81], v[52:53]
	v_cvt_pk_bf16_f32 v52, v48, v49
	v_cvt_pk_bf16_f32 v53, v50, v51
	v_cvt_pk_bf16_f32 v48, v98, v99
	v_cvt_pk_bf16_f32 v49, v104, v105
	s_waitcnt lgkmcnt(0)
	v_mfma_f32_32x32x16_bf16 v[16:31], v[64:67], v[52:55], v[16:31]
	ds_read_b128 v[64:67], v72 offset:96
	v_cvt_pk_bf16_f32 v50, v106, v107
	v_cvt_pk_bf16_f32 v51, v108, v109
	s_cmp_lg_u32 s40, 2
	s_cselect_b32 s40, s40, 0
	s_addk_i32 s90, 0x7c
	s_add_u32 s86, s86, 0x80
	s_waitcnt lgkmcnt(0)
	v_mfma_f32_32x32x16_bf16 v[16:31], v[64:67], v[48:51], v[16:31]
	s_mov_b64 s[94:95], 0x82000
	s_addc_u32 s87, s87, 0
	s_add_i32 s46, s46, 1
	v_lshl_add_u64 v[182:183], v[182:183], 0, s[94:95]
	s_cmp_lg_u32 s90, 0
	s_waitcnt lgkmcnt(0)
	v_mfma_f32_32x32x16_bf16 v[0:15], v[240:243], v[56:59], v[0:15]
	s_waitcnt lgkmcnt(0)
	v_mfma_f32_32x32x16_bf16 v[0:15], v[244:247], v[60:63], v[0:15]
	s_waitcnt lgkmcnt(0)
	v_mfma_f32_32x32x16_bf16 v[0:15], v[248:251], v[52:55], v[0:15]
	s_waitcnt lgkmcnt(0)
	s_barrier
	s_waitcnt lgkmcnt(0)
	v_mfma_f32_32x32x16_bf16 v[0:15], v[252:255], v[48:51], v[0:15]
	s_cbranch_scc0 .LBB0_822
	s_mov_b32 s89, s91
	s_mov_b32 s91, s40
	v_mov_b32_e32 v180, v80
	s_branch .LBB0_748

.LBB0_882:
	v_mov_b32_e32 v32, v206
	v_mov_b32_e32 v35, 0
	v_and_b32_e32 v1, 0x7f, v32
	v_and_b32_e32 v0, 0xffffff80, v32
	v_lshlrev_b32_e32 v192, 1, v1
	v_readfirstlane_b32 s84, v32
	v_lshl_add_u32 v36, v0, 15, v192
	s_mov_b64 s[48:49], 0
	global_load_ushort v40, v36, s[46:47]
	global_load_ushort v41, v36, s[6:7]
	global_load_ushort v42, v36, s[8:9]
	global_load_ushort v43, v36, s[16:17]
	global_load_ushort v44, v36, s[18:19]
	global_load_ushort v45, v36, s[20:21]
	global_load_ushort v46, v36, s[22:23]
	global_load_ushort v47, v36, s[24:25]
	global_load_ushort v48, v36, s[26:27]
	global_load_ushort v49, v36, s[28:29]
	global_load_ushort v50, v36, s[30:31]
	global_load_ushort v51, v36, s[34:35]
	global_load_ushort v52, v36, s[36:37]
	global_load_ushort v53, v36, s[38:39]
	global_load_ushort v54, v36, s[42:43]
	global_load_ushort v55, v36, s[44:45]
	v_add_u32_e32 v37, 0x80000, v36
	global_load_ushort v56, v37, s[46:47]
	global_load_ushort v57, v37, s[6:7]
	global_load_ushort v58, v37, s[8:9]
	global_load_ushort v59, v37, s[16:17]
	global_load_ushort v60, v37, s[18:19]
	global_load_ushort v61, v37, s[20:21]
	global_load_ushort v62, v37, s[22:23]
	global_load_ushort v63, v37, s[24:25]
	global_load_ushort v64, v37, s[26:27]
	global_load_ushort v65, v37, s[28:29]
	global_load_ushort v66, v37, s[30:31]
	global_load_ushort v67, v37, s[34:35]
	global_load_ushort v68, v37, s[36:37]
	global_load_ushort v69, v37, s[38:39]
	global_load_ushort v70, v37, s[42:43]
	global_load_ushort v71, v37, s[44:45]
	v_add_u32_e32 v37, 0x100000, v36
	global_load_ushort v72, v37, s[46:47]
	global_load_ushort v73, v37, s[6:7]
	global_load_ushort v74, v37, s[8:9]
	global_load_ushort v75, v37, s[16:17]
	global_load_ushort v76, v37, s[18:19]
	global_load_ushort v77, v37, s[20:21]
	global_load_ushort v78, v37, s[22:23]
	global_load_ushort v79, v37, s[24:25]
	global_load_ushort v80, v37, s[26:27]
	global_load_ushort v81, v37, s[28:29]
	global_load_ushort v82, v37, s[30:31]
	global_load_ushort v83, v37, s[34:35]
	global_load_ushort v84, v37, s[36:37]
	global_load_ushort v85, v37, s[38:39]
	global_load_ushort v86, v37, s[42:43]
	global_load_ushort v87, v37, s[44:45]
	s_waitcnt vmcnt(32)
	v_lshlrev_b32_e32 v40, 16, v40
	v_fmac_f32_e32 v35, v40, v40
	v_lshlrev_b32_e32 v41, 16, v41
	v_fmac_f32_e32 v35, v41, v41
	v_lshlrev_b32_e32 v42, 16, v42
	v_fmac_f32_e32 v35, v42, v42
	v_lshlrev_b32_e32 v43, 16, v43
	v_fmac_f32_e32 v35, v43, v43
	v_lshlrev_b32_e32 v44, 16, v44
	v_fmac_f32_e32 v35, v44, v44
	v_lshlrev_b32_e32 v45, 16, v45
	v_fmac_f32_e32 v35, v45, v45
	v_lshlrev_b32_e32 v46, 16, v46
	v_fmac_f32_e32 v35, v46, v46
	v_lshlrev_b32_e32 v47, 16, v47
	v_fmac_f32_e32 v35, v47, v47
	v_lshlrev_b32_e32 v48, 16, v48
	v_fmac_f32_e32 v35, v48, v48
	v_lshlrev_b32_e32 v49, 16, v49
	v_fmac_f32_e32 v35, v49, v49
	v_lshlrev_b32_e32 v50, 16, v50
	v_fmac_f32_e32 v35, v50, v50
	v_lshlrev_b32_e32 v51, 16, v51
	v_fmac_f32_e32 v35, v51, v51
	v_lshlrev_b32_e32 v52, 16, v52
	v_fmac_f32_e32 v35, v52, v52
	v_lshlrev_b32_e32 v53, 16, v53
	v_fmac_f32_e32 v35, v53, v53
	v_lshlrev_b32_e32 v54, 16, v54
	v_fmac_f32_e32 v35, v54, v54
	v_lshlrev_b32_e32 v55, 16, v55
	v_fmac_f32_e32 v35, v55, v55
	v_add_u32_e32 v37, 0x180000, v36
	global_load_ushort v40, v37, s[46:47]
	global_load_ushort v41, v37, s[6:7]
	global_load_ushort v42, v37, s[8:9]
	global_load_ushort v43, v37, s[16:17]
	global_load_ushort v44, v37, s[18:19]
	global_load_ushort v45, v37, s[20:21]
	global_load_ushort v46, v37, s[22:23]
	global_load_ushort v47, v37, s[24:25]
	global_load_ushort v48, v37, s[26:27]
	global_load_ushort v49, v37, s[28:29]
	global_load_ushort v50, v37, s[30:31]
	global_load_ushort v51, v37, s[34:35]
	global_load_ushort v52, v37, s[36:37]
	global_load_ushort v53, v37, s[38:39]
	global_load_ushort v54, v37, s[42:43]
	global_load_ushort v55, v37, s[44:45]
	s_waitcnt vmcnt(32)
	v_lshlrev_b32_e32 v56, 16, v56
	v_fmac_f32_e32 v35, v56, v56
	v_lshlrev_b32_e32 v57, 16, v57
	v_fmac_f32_e32 v35, v57, v57
	v_lshlrev_b32_e32 v58, 16, v58
	v_fmac_f32_e32 v35, v58, v58
	v_lshlrev_b32_e32 v59, 16, v59
	v_fmac_f32_e32 v35, v59, v59
	v_lshlrev_b32_e32 v60, 16, v60
	v_fmac_f32_e32 v35, v60, v60
	v_lshlrev_b32_e32 v61, 16, v61
	v_fmac_f32_e32 v35, v61, v61
	v_lshlrev_b32_e32 v62, 16, v62
	v_fmac_f32_e32 v35, v62, v62
	v_lshlrev_b32_e32 v63, 16, v63
	v_fmac_f32_e32 v35, v63, v63
	v_lshlrev_b32_e32 v64, 16, v64
	v_fmac_f32_e32 v35, v64, v64
	v_lshlrev_b32_e32 v65, 16, v65
	v_fmac_f32_e32 v35, v65, v65
	v_lshlrev_b32_e32 v66, 16, v66
	v_fmac_f32_e32 v35, v66, v66
	v_lshlrev_b32_e32 v67, 16, v67
	v_fmac_f32_e32 v35, v67, v67
	v_lshlrev_b32_e32 v68, 16, v68
	v_fmac_f32_e32 v35, v68, v68
	v_lshlrev_b32_e32 v69, 16, v69
	v_fmac_f32_e32 v35, v69, v69
	v_lshlrev_b32_e32 v70, 16, v70
	v_fmac_f32_e32 v35, v70, v70
	v_lshlrev_b32_e32 v71, 16, v71
	v_fmac_f32_e32 v35, v71, v71
	v_add_u32_e32 v37, 0x200000, v36
	global_load_ushort v56, v37, s[46:47]
	global_load_ushort v57, v37, s[6:7]
	global_load_ushort v58, v37, s[8:9]
	global_load_ushort v59, v37, s[16:17]
	global_load_ushort v60, v37, s[18:19]
	global_load_ushort v61, v37, s[20:21]
	global_load_ushort v62, v37, s[22:23]
	global_load_ushort v63, v37, s[24:25]
	global_load_ushort v64, v37, s[26:27]
	global_load_ushort v65, v37, s[28:29]
	global_load_ushort v66, v37, s[30:31]
	global_load_ushort v67, v37, s[34:35]
	global_load_ushort v68, v37, s[36:37]
	global_load_ushort v69, v37, s[38:39]
	global_load_ushort v70, v37, s[42:43]
	global_load_ushort v71, v37, s[44:45]
	s_waitcnt vmcnt(32)
	v_lshlrev_b32_e32 v72, 16, v72
	v_fmac_f32_e32 v35, v72, v72
	v_lshlrev_b32_e32 v73, 16, v73
	v_fmac_f32_e32 v35, v73, v73
	v_lshlrev_b32_e32 v74, 16, v74
	v_fmac_f32_e32 v35, v74, v74
	v_lshlrev_b32_e32 v75, 16, v75
	v_fmac_f32_e32 v35, v75, v75
	v_lshlrev_b32_e32 v76, 16, v76
	v_fmac_f32_e32 v35, v76, v76
	v_lshlrev_b32_e32 v77, 16, v77
	v_fmac_f32_e32 v35, v77, v77
	v_lshlrev_b32_e32 v78, 16, v78
	v_fmac_f32_e32 v35, v78, v78
	v_lshlrev_b32_e32 v79, 16, v79
	v_fmac_f32_e32 v35, v79, v79
	v_lshlrev_b32_e32 v80, 16, v80
	v_fmac_f32_e32 v35, v80, v80
	v_lshlrev_b32_e32 v81, 16, v81
	v_fmac_f32_e32 v35, v81, v81
	v_lshlrev_b32_e32 v82, 16, v82
	v_fmac_f32_e32 v35, v82, v82
	v_lshlrev_b32_e32 v83, 16, v83
	v_fmac_f32_e32 v35, v83, v83
	v_lshlrev_b32_e32 v84, 16, v84
	v_fmac_f32_e32 v35, v84, v84
	v_lshlrev_b32_e32 v85, 16, v85
	v_fmac_f32_e32 v35, v85, v85
	v_lshlrev_b32_e32 v86, 16, v86
	v_fmac_f32_e32 v35, v86, v86
	v_lshlrev_b32_e32 v87, 16, v87
	v_fmac_f32_e32 v35, v87, v87
	v_add_u32_e32 v37, 0x280000, v36
	global_load_ushort v72, v37, s[46:47]
	global_load_ushort v73, v37, s[6:7]
	global_load_ushort v74, v37, s[8:9]
	global_load_ushort v75, v37, s[16:17]
	global_load_ushort v76, v37, s[18:19]
	global_load_ushort v77, v37, s[20:21]
	global_load_ushort v78, v37, s[22:23]
	global_load_ushort v79, v37, s[24:25]
	global_load_ushort v80, v37, s[26:27]
	global_load_ushort v81, v37, s[28:29]
	global_load_ushort v82, v37, s[30:31]
	global_load_ushort v83, v37, s[34:35]
	global_load_ushort v84, v37, s[36:37]
	global_load_ushort v85, v37, s[38:39]
	global_load_ushort v86, v37, s[42:43]
	global_load_ushort v87, v37, s[44:45]
	s_waitcnt vmcnt(32)
	v_lshlrev_b32_e32 v40, 16, v40
	v_fmac_f32_e32 v35, v40, v40
	v_lshlrev_b32_e32 v41, 16, v41
	v_fmac_f32_e32 v35, v41, v41
	v_lshlrev_b32_e32 v42, 16, v42
	v_fmac_f32_e32 v35, v42, v42
	v_lshlrev_b32_e32 v43, 16, v43
	v_fmac_f32_e32 v35, v43, v43
	v_lshlrev_b32_e32 v44, 16, v44
	v_fmac_f32_e32 v35, v44, v44
	v_lshlrev_b32_e32 v45, 16, v45
	v_fmac_f32_e32 v35, v45, v45
	v_lshlrev_b32_e32 v46, 16, v46
	v_fmac_f32_e32 v35, v46, v46
	v_lshlrev_b32_e32 v47, 16, v47
	v_fmac_f32_e32 v35, v47, v47
	v_lshlrev_b32_e32 v48, 16, v48
	v_fmac_f32_e32 v35, v48, v48
	v_lshlrev_b32_e32 v49, 16, v49
	v_fmac_f32_e32 v35, v49, v49
	v_lshlrev_b32_e32 v50, 16, v50
	v_fmac_f32_e32 v35, v50, v50
	v_lshlrev_b32_e32 v51, 16, v51
	v_fmac_f32_e32 v35, v51, v51
	v_lshlrev_b32_e32 v52, 16, v52
	v_fmac_f32_e32 v35, v52, v52
	v_lshlrev_b32_e32 v53, 16, v53
	v_fmac_f32_e32 v35, v53, v53
	v_lshlrev_b32_e32 v54, 16, v54
	v_fmac_f32_e32 v35, v54, v54
	v_lshlrev_b32_e32 v55, 16, v55
	v_fmac_f32_e32 v35, v55, v55
	v_add_u32_e32 v37, 0x300000, v36
	global_load_ushort v40, v37, s[46:47]
	global_load_ushort v41, v37, s[6:7]
	global_load_ushort v42, v37, s[8:9]
	global_load_ushort v43, v37, s[16:17]
	global_load_ushort v44, v37, s[18:19]
	global_load_ushort v45, v37, s[20:21]
	global_load_ushort v46, v37, s[22:23]
	global_load_ushort v47, v37, s[24:25]
	global_load_ushort v48, v37, s[26:27]
	global_load_ushort v49, v37, s[28:29]
	global_load_ushort v50, v37, s[30:31]
	global_load_ushort v51, v37, s[34:35]
	global_load_ushort v52, v37, s[36:37]
	global_load_ushort v53, v37, s[38:39]
	global_load_ushort v54, v37, s[42:43]
	global_load_ushort v55, v37, s[44:45]
	s_waitcnt vmcnt(32)
	v_lshlrev_b32_e32 v56, 16, v56
	v_fmac_f32_e32 v35, v56, v56
	v_lshlrev_b32_e32 v57, 16, v57
	v_fmac_f32_e32 v35, v57, v57
	v_lshlrev_b32_e32 v58, 16, v58
	v_fmac_f32_e32 v35, v58, v58
	v_lshlrev_b32_e32 v59, 16, v59
	v_fmac_f32_e32 v35, v59, v59
	v_lshlrev_b32_e32 v60, 16, v60
	v_fmac_f32_e32 v35, v60, v60
	v_lshlrev_b32_e32 v61, 16, v61
	v_fmac_f32_e32 v35, v61, v61
	v_lshlrev_b32_e32 v62, 16, v62
	v_fmac_f32_e32 v35, v62, v62
	v_lshlrev_b32_e32 v63, 16, v63
	v_fmac_f32_e32 v35, v63, v63
	v_lshlrev_b32_e32 v64, 16, v64
	v_fmac_f32_e32 v35, v64, v64
	v_lshlrev_b32_e32 v65, 16, v65
	v_fmac_f32_e32 v35, v65, v65
	v_lshlrev_b32_e32 v66, 16, v66
	v_fmac_f32_e32 v35, v66, v66
	v_lshlrev_b32_e32 v67, 16, v67
	v_fmac_f32_e32 v35, v67, v67
	v_lshlrev_b32_e32 v68, 16, v68
	v_fmac_f32_e32 v35, v68, v68
	v_lshlrev_b32_e32 v69, 16, v69
	v_fmac_f32_e32 v35, v69, v69
	v_lshlrev_b32_e32 v70, 16, v70
	v_fmac_f32_e32 v35, v70, v70
	v_lshlrev_b32_e32 v71, 16, v71
	v_fmac_f32_e32 v35, v71, v71
	v_add_u32_e32 v37, 0x380000, v36
	global_load_ushort v56, v37, s[46:47]
	global_load_ushort v57, v37, s[6:7]
	global_load_ushort v58, v37, s[8:9]
	global_load_ushort v59, v37, s[16:17]
	global_load_ushort v60, v37, s[18:19]
	global_load_ushort v61, v37, s[20:21]
	global_load_ushort v62, v37, s[22:23]
	global_load_ushort v63, v37, s[24:25]
	global_load_ushort v64, v37, s[26:27]
	global_load_ushort v65, v37, s[28:29]
	global_load_ushort v66, v37, s[30:31]
	global_load_ushort v67, v37, s[34:35]
	global_load_ushort v68, v37, s[36:37]
	global_load_ushort v69, v37, s[38:39]
	global_load_ushort v70, v37, s[42:43]
	global_load_ushort v71, v37, s[44:45]
	s_waitcnt vmcnt(32)
	v_lshlrev_b32_e32 v72, 16, v72
	v_fmac_f32_e32 v35, v72, v72
	v_lshlrev_b32_e32 v73, 16, v73
	v_fmac_f32_e32 v35, v73, v73
	v_lshlrev_b32_e32 v74, 16, v74
	v_fmac_f32_e32 v35, v74, v74
	v_lshlrev_b32_e32 v75, 16, v75
	v_fmac_f32_e32 v35, v75, v75
	v_lshlrev_b32_e32 v76, 16, v76
	v_fmac_f32_e32 v35, v76, v76
	v_lshlrev_b32_e32 v77, 16, v77
	v_fmac_f32_e32 v35, v77, v77
	v_lshlrev_b32_e32 v78, 16, v78
	v_fmac_f32_e32 v35, v78, v78
	v_lshlrev_b32_e32 v79, 16, v79
	v_fmac_f32_e32 v35, v79, v79
	v_lshlrev_b32_e32 v80, 16, v80
	v_fmac_f32_e32 v35, v80, v80
	v_lshlrev_b32_e32 v81, 16, v81
	v_fmac_f32_e32 v35, v81, v81
	v_lshlrev_b32_e32 v82, 16, v82
	v_fmac_f32_e32 v35, v82, v82
	v_lshlrev_b32_e32 v83, 16, v83
	v_fmac_f32_e32 v35, v83, v83
	v_lshlrev_b32_e32 v84, 16, v84
	v_fmac_f32_e32 v35, v84, v84
	v_lshlrev_b32_e32 v85, 16, v85
	v_fmac_f32_e32 v35, v85, v85
	v_lshlrev_b32_e32 v86, 16, v86
	v_fmac_f32_e32 v35, v86, v86
	v_lshlrev_b32_e32 v87, 16, v87
	v_fmac_f32_e32 v35, v87, v87
	s_waitcnt vmcnt(16)
	v_lshlrev_b32_e32 v40, 16, v40
	v_fmac_f32_e32 v35, v40, v40
	v_lshlrev_b32_e32 v41, 16, v41
	v_fmac_f32_e32 v35, v41, v41
	v_lshlrev_b32_e32 v42, 16, v42
	v_fmac_f32_e32 v35, v42, v42
	v_lshlrev_b32_e32 v43, 16, v43
	v_fmac_f32_e32 v35, v43, v43
	v_lshlrev_b32_e32 v44, 16, v44
	v_fmac_f32_e32 v35, v44, v44
	v_lshlrev_b32_e32 v45, 16, v45
	v_fmac_f32_e32 v35, v45, v45
	v_lshlrev_b32_e32 v46, 16, v46
	v_fmac_f32_e32 v35, v46, v46
	v_lshlrev_b32_e32 v47, 16, v47
	v_fmac_f32_e32 v35, v47, v47
	v_lshlrev_b32_e32 v48, 16, v48
	v_fmac_f32_e32 v35, v48, v48
	v_lshlrev_b32_e32 v49, 16, v49
	v_fmac_f32_e32 v35, v49, v49
	v_lshlrev_b32_e32 v50, 16, v50
	v_fmac_f32_e32 v35, v50, v50
	v_lshlrev_b32_e32 v51, 16, v51
	v_fmac_f32_e32 v35, v51, v51
	v_lshlrev_b32_e32 v52, 16, v52
	v_fmac_f32_e32 v35, v52, v52
	v_lshlrev_b32_e32 v53, 16, v53
	v_fmac_f32_e32 v35, v53, v53
	v_lshlrev_b32_e32 v54, 16, v54
	v_fmac_f32_e32 v35, v54, v54
	v_lshlrev_b32_e32 v55, 16, v55
	v_fmac_f32_e32 v35, v55, v55
	s_waitcnt vmcnt(0)
	v_lshlrev_b32_e32 v56, 16, v56
	v_fmac_f32_e32 v35, v56, v56
	v_lshlrev_b32_e32 v57, 16, v57
	v_fmac_f32_e32 v35, v57, v57
	v_lshlrev_b32_e32 v58, 16, v58
	v_fmac_f32_e32 v35, v58, v58
	v_lshlrev_b32_e32 v59, 16, v59
	v_fmac_f32_e32 v35, v59, v59
	v_lshlrev_b32_e32 v60, 16, v60
	v_fmac_f32_e32 v35, v60, v60
	v_lshlrev_b32_e32 v61, 16, v61
	v_fmac_f32_e32 v35, v61, v61
	v_lshlrev_b32_e32 v62, 16, v62
	v_fmac_f32_e32 v35, v62, v62
	v_lshlrev_b32_e32 v63, 16, v63
	v_fmac_f32_e32 v35, v63, v63
	v_lshlrev_b32_e32 v64, 16, v64
	v_fmac_f32_e32 v35, v64, v64
	v_lshlrev_b32_e32 v65, 16, v65
	v_fmac_f32_e32 v35, v65, v65
	v_lshlrev_b32_e32 v66, 16, v66
	v_fmac_f32_e32 v35, v66, v66
	v_lshlrev_b32_e32 v67, 16, v67
	v_fmac_f32_e32 v35, v67, v67
	v_lshlrev_b32_e32 v68, 16, v68
	v_fmac_f32_e32 v35, v68, v68
	v_lshlrev_b32_e32 v69, 16, v69
	v_fmac_f32_e32 v35, v69, v69
	v_lshlrev_b32_e32 v70, 16, v70
	v_fmac_f32_e32 v35, v70, v70
	v_lshlrev_b32_e32 v71, 16, v71
	v_fmac_f32_e32 v35, v71, v71
